# stack21: stack19 + branch / output-projection weight conversions moved from the conversion phase into the GLU-phase tail (spare CUs)
# speedup vs baseline: 1.0074x; 1.0074x over previous
.LBB0_70:
	s_waitcnt lgkmcnt(0)
	s_add_u32 s4, s96, 0x1dda9800
	s_addc_u32 s5, s97, 0
	v_writelane_b32 v250, s4, 60
	s_nop 1
	v_writelane_b32 v250, s5, 61
	s_mov_b32 s4, 0x20000
	v_cmp_gt_i32_e64 s[42:43], s4, v16
	s_and_saveexec_b64 s[4:5], s[42:43]
	s_cbranch_execz .LBB0_89
	s_branch .LBB0_89
	s_load_dwordx2 s[8:9], s[26:27], 0x100
	v_readlane_b32 s6, v250, 58
	v_readlane_b32 s7, v250, 59
	s_lshl_b64 s[10:11], s[6:7], 22
	s_mov_b64 s[6:7], 0
	s_waitcnt lgkmcnt(0)
	s_add_u32 s8, s8, s10
	s_addc_u32 s9, s9, s11
	v_mov_b32_e32 v4, v16
	s_branch .LBB0_73

.LBB0_932:
	s_add_u32 s16, s14, 0xfffe0080
	s_addc_u32 s17, s15, -1
	s_add_i32 s50, 0, 0x10000
	v_add_u32_e32 v150, s50, v144
	ds_read_b128 v[134:137], v150
	ds_read_b128 v[138:141], v150 offset:1024
	ds_read_b128 v[146:149], v150 offset:2048
	ds_read_b128 v[150:153], v150 offset:3072
	s_cmp_eq_u32 s49, 4
	s_cselect_b32 s19, s11, s17
	s_cselect_b32 s18, s10, s16
	s_cselect_b32 s17, s13, s9
	s_cselect_b32 s16, s12, s7
	v_lshl_add_u64 v[174:175], s[14:15], 0, v[130:131]
	s_add_i32 m0, s3, 0xc000
	ds_read_b128 v[154:157], v145
	ds_read_b128 v[158:161], v145 offset:1024
	ds_read_b128 v[162:165], v145 offset:2048
	ds_read_b128 v[166:169], v145 offset:3072
	ds_read_b128 v[170:173], v145 offset:4096
	ds_read_b128 v[190:193], v145 offset:5120
	ds_read_b128 v[194:197], v145 offset:6144
	ds_read_b128 v[198:201], v145 offset:7168
	global_load_lds_dwordx4 v[174:175], off
	v_lshl_add_u64 v[174:175], s[14:15], 0, v[132:133]
	s_add_i32 m0, s3, 0xe000
	s_nop 0
	global_load_lds_dwordx4 v[174:175], off
	s_waitcnt lgkmcnt(8)
	s_barrier
	s_waitcnt lgkmcnt(0)
	s_setprio 1
	s_waitcnt lgkmcnt(0)
	v_mfma_f32_16x16x32_bf16 v[124:127], v[134:137], v[154:157], v[124:127]
	v_mfma_f32_16x16x32_bf16 v[120:123], v[146:149], v[154:157], v[120:123]
	v_mfma_f32_16x16x32_bf16 v[108:111], v[134:137], v[162:165], v[108:111]
	v_mfma_f32_16x16x32_bf16 v[104:107], v[146:149], v[162:165], v[104:107]
	v_mfma_f32_16x16x32_bf16 v[92:95], v[134:137], v[170:173], v[92:95]
	v_mfma_f32_16x16x32_bf16 v[88:91], v[146:149], v[170:173], v[88:91]
	v_mfma_f32_16x16x32_bf16 v[76:79], v[134:137], v[194:197], v[76:79]
	v_mfma_f32_16x16x32_bf16 v[72:75], v[146:149], v[194:197], v[72:75]
	v_mfma_f32_16x16x32_bf16 v[124:127], v[138:141], v[158:161], v[124:127]
	v_mfma_f32_16x16x32_bf16 v[120:123], v[150:153], v[158:161], v[120:123]
	v_mfma_f32_16x16x32_bf16 v[108:111], v[138:141], v[166:169], v[108:111]
	v_mfma_f32_16x16x32_bf16 v[104:107], v[150:153], v[166:169], v[104:107]
	v_mfma_f32_16x16x32_bf16 v[92:95], v[138:141], v[190:193], v[92:95]
	v_mfma_f32_16x16x32_bf16 v[88:91], v[150:153], v[190:193], v[88:91]
	v_mfma_f32_16x16x32_bf16 v[76:79], v[138:141], v[198:201], v[76:79]
	v_mfma_f32_16x16x32_bf16 v[72:75], v[150:153], v[198:201], v[72:75]
	s_setprio 0
	s_barrier
	s_add_i32 s52, 0, 0x14000
	v_add_u32_e32 v174, s52, v144
	s_add_i32 s50, s50, s38
	ds_read_b128 v[202:205], v174
	ds_read_b128 v[206:209], v174 offset:1024
	ds_read_b128 v[210:213], v174 offset:2048
	ds_read_b128 v[214:217], v174 offset:3072
	v_lshl_add_u64 v[174:175], s[16:17], 0, v[176:177]
	s_mov_b32 m0, s50
	v_lshl_add_u64 v[218:219], s[16:17], 0, v[128:129]
	global_load_lds_dwordx4 v[174:175], off
	s_add_i32 m0, s50, 0x2000
	s_nop 0
	global_load_lds_dwordx4 v[218:219], off
	s_barrier
	s_waitcnt lgkmcnt(0)
	s_setprio 1
	s_waitcnt lgkmcnt(0)
	v_mfma_f32_16x16x32_bf16 v[116:119], v[202:205], v[154:157], v[116:119]
	v_mfma_f32_16x16x32_bf16 v[112:115], v[210:213], v[154:157], v[112:115]
	v_mfma_f32_16x16x32_bf16 v[100:103], v[202:205], v[162:165], v[100:103]
	v_mfma_f32_16x16x32_bf16 v[96:99], v[210:213], v[162:165], v[96:99]
	v_mfma_f32_16x16x32_bf16 v[84:87], v[202:205], v[170:173], v[84:87]
	v_mfma_f32_16x16x32_bf16 v[80:83], v[210:213], v[170:173], v[80:83]
	v_mfma_f32_16x16x32_bf16 v[68:71], v[202:205], v[194:197], v[68:71]
	v_mfma_f32_16x16x32_bf16 v[64:67], v[210:213], v[194:197], v[64:67]
	v_mfma_f32_16x16x32_bf16 v[116:119], v[206:209], v[158:161], v[116:119]
	v_mfma_f32_16x16x32_bf16 v[112:115], v[214:217], v[158:161], v[112:115]
	v_mfma_f32_16x16x32_bf16 v[100:103], v[206:209], v[166:169], v[100:103]
	v_mfma_f32_16x16x32_bf16 v[96:99], v[214:217], v[166:169], v[96:99]
	v_mfma_f32_16x16x32_bf16 v[84:87], v[206:209], v[190:193], v[84:87]
	v_mfma_f32_16x16x32_bf16 v[80:83], v[214:217], v[190:193], v[80:83]
	v_mfma_f32_16x16x32_bf16 v[68:71], v[206:209], v[198:201], v[68:71]
	v_mfma_f32_16x16x32_bf16 v[64:67], v[214:217], v[198:201], v[64:67]
	s_setprio 0
	s_mov_b32 m0, s3
	v_lshl_add_u64 v[220:221], s[18:19], 0, v[176:177]
	s_barrier
	ds_read_b128 v[154:157], v145 offset:16384
	ds_read_b128 v[158:161], v145 offset:17408
	ds_read_b128 v[162:165], v145 offset:18432
	ds_read_b128 v[166:169], v145 offset:19456
	ds_read_b128 v[170:173], v145 offset:20480
	ds_read_b128 v[190:193], v145 offset:21504
	ds_read_b128 v[194:197], v145 offset:22528
	ds_read_b128 v[198:201], v145 offset:23552
	global_load_lds_dwordx4 v[220:221], off
	v_lshl_add_u64 v[222:223], s[18:19], 0, v[128:129]
	s_mov_b32 m0, s39
	s_nop 0
	global_load_lds_dwordx4 v[222:223], off
	s_barrier
	s_waitcnt lgkmcnt(0)
	s_setprio 1
	s_waitcnt lgkmcnt(0)
	v_mfma_f32_16x16x32_bf16 v[60:63], v[134:137], v[154:157], v[60:63]
	v_mfma_f32_16x16x32_bf16 v[56:59], v[146:149], v[154:157], v[56:59]
	v_mfma_f32_16x16x32_bf16 v[44:47], v[134:137], v[162:165], v[44:47]
	v_mfma_f32_16x16x32_bf16 v[40:43], v[146:149], v[162:165], v[40:43]
	v_mfma_f32_16x16x32_bf16 v[28:31], v[134:137], v[170:173], v[28:31]
	v_mfma_f32_16x16x32_bf16 v[24:27], v[146:149], v[170:173], v[24:27]
	v_mfma_f32_16x16x32_bf16 v[12:15], v[134:137], v[194:197], v[12:15]
	v_mfma_f32_16x16x32_bf16 v[8:11], v[146:149], v[194:197], v[8:11]
	v_mfma_f32_16x16x32_bf16 v[60:63], v[138:141], v[158:161], v[60:63]
	v_mfma_f32_16x16x32_bf16 v[56:59], v[150:153], v[158:161], v[56:59]
	v_mfma_f32_16x16x32_bf16 v[44:47], v[138:141], v[166:169], v[44:47]
	v_mfma_f32_16x16x32_bf16 v[40:43], v[150:153], v[166:169], v[40:43]
	v_mfma_f32_16x16x32_bf16 v[28:31], v[138:141], v[190:193], v[28:31]
	v_mfma_f32_16x16x32_bf16 v[24:27], v[150:153], v[190:193], v[24:27]
	v_mfma_f32_16x16x32_bf16 v[12:15], v[138:141], v[198:201], v[12:15]
	v_mfma_f32_16x16x32_bf16 v[8:11], v[150:153], v[198:201], v[8:11]
	s_setprio 0
	s_barrier
	s_add_u32 s50, s16, 0x20000
	s_addc_u32 s51, s17, 0
	s_add_i32 s52, s52, s38
	v_lshl_add_u64 v[134:135], s[50:51], 0, v[176:177]
	s_mov_b32 m0, s52
	s_nop 0
	global_load_lds_dwordx4 v[134:135], off
	v_lshl_add_u64 v[134:135], s[50:51], 0, v[128:129]
	s_add_i32 m0, s52, 0x2000
	s_nop 0
	global_load_lds_dwordx4 v[134:135], off
	s_waitcnt vmcnt(6)
	s_barrier
	s_setprio 1
	v_mfma_f32_16x16x32_bf16 v[52:55], v[202:205], v[154:157], v[52:55]
	v_mfma_f32_16x16x32_bf16 v[48:51], v[210:213], v[154:157], v[48:51]
	v_mfma_f32_16x16x32_bf16 v[36:39], v[202:205], v[162:165], v[36:39]
	v_mfma_f32_16x16x32_bf16 v[32:35], v[210:213], v[162:165], v[32:35]
	v_mfma_f32_16x16x32_bf16 v[20:23], v[202:205], v[170:173], v[20:23]
	v_mfma_f32_16x16x32_bf16 v[16:19], v[210:213], v[170:173], v[16:19]
	v_mfma_f32_16x16x32_bf16 v[4:7], v[202:205], v[194:197], v[4:7]
	v_mfma_f32_16x16x32_bf16 v[0:3], v[210:213], v[194:197], v[0:3]
	v_mfma_f32_16x16x32_bf16 v[52:55], v[206:209], v[158:161], v[52:55]
	v_mfma_f32_16x16x32_bf16 v[48:51], v[214:217], v[158:161], v[48:51]
	v_mfma_f32_16x16x32_bf16 v[36:39], v[206:209], v[166:169], v[36:39]
	v_mfma_f32_16x16x32_bf16 v[32:35], v[214:217], v[166:169], v[32:35]
	v_mfma_f32_16x16x32_bf16 v[20:23], v[206:209], v[190:193], v[20:23]
	v_mfma_f32_16x16x32_bf16 v[16:19], v[214:217], v[190:193], v[16:19]
	v_mfma_f32_16x16x32_bf16 v[4:7], v[206:209], v[198:201], v[4:7]
	v_mfma_f32_16x16x32_bf16 v[0:3], v[214:217], v[198:201], v[0:3]
	s_setprio 0
	s_add_i32 s50, 0, 0x18000
	v_add_u32_e32 v150, s50, v144
	s_barrier
	ds_read_b128 v[134:137], v150
	ds_read_b128 v[138:141], v150 offset:1024
	ds_read_b128 v[146:149], v150 offset:2048
	ds_read_b128 v[150:153], v150 offset:3072
	s_add_u32 s18, s18, 0x20000
	s_addc_u32 s19, s19, 0
	s_mov_b32 m0, s42
	v_lshl_add_u64 v[202:203], s[18:19], 0, v[176:177]
	ds_read_b128 v[154:157], v145 offset:32768
	ds_read_b128 v[158:161], v145 offset:33792
	ds_read_b128 v[162:165], v145 offset:34816
	ds_read_b128 v[166:169], v145 offset:35840
	ds_read_b128 v[170:173], v145 offset:36864
	ds_read_b128 v[190:193], v145 offset:37888
	ds_read_b128 v[194:197], v145 offset:38912
	ds_read_b128 v[198:201], v145 offset:39936
	global_load_lds_dwordx4 v[202:203], off
	v_lshl_add_u64 v[202:203], s[18:19], 0, v[128:129]
	s_mov_b32 m0, s43
	s_nop 0
	global_load_lds_dwordx4 v[202:203], off
	s_waitcnt lgkmcnt(8)
	s_barrier
	s_waitcnt lgkmcnt(0)
	s_setprio 1
	s_waitcnt lgkmcnt(0)
	v_mfma_f32_16x16x32_bf16 v[124:127], v[134:137], v[154:157], v[124:127]
	v_mfma_f32_16x16x32_bf16 v[120:123], v[146:149], v[154:157], v[120:123]
	v_mfma_f32_16x16x32_bf16 v[108:111], v[134:137], v[162:165], v[108:111]
	v_mfma_f32_16x16x32_bf16 v[104:107], v[146:149], v[162:165], v[104:107]
	v_mfma_f32_16x16x32_bf16 v[92:95], v[134:137], v[170:173], v[92:95]
	v_mfma_f32_16x16x32_bf16 v[88:91], v[146:149], v[170:173], v[88:91]
	v_mfma_f32_16x16x32_bf16 v[76:79], v[134:137], v[194:197], v[76:79]
	v_mfma_f32_16x16x32_bf16 v[72:75], v[146:149], v[194:197], v[72:75]
	v_mfma_f32_16x16x32_bf16 v[124:127], v[138:141], v[158:161], v[124:127]
	v_mfma_f32_16x16x32_bf16 v[120:123], v[150:153], v[158:161], v[120:123]
	v_mfma_f32_16x16x32_bf16 v[108:111], v[138:141], v[166:169], v[108:111]
	v_mfma_f32_16x16x32_bf16 v[104:107], v[150:153], v[166:169], v[104:107]
	v_mfma_f32_16x16x32_bf16 v[92:95], v[138:141], v[190:193], v[92:95]
	v_mfma_f32_16x16x32_bf16 v[88:91], v[150:153], v[190:193], v[88:91]
	v_mfma_f32_16x16x32_bf16 v[76:79], v[138:141], v[198:201], v[76:79]
	v_mfma_f32_16x16x32_bf16 v[72:75], v[150:153], v[198:201], v[72:75]
	s_setprio 0
	s_barrier
	s_add_i32 s18, 0, 0x1c000
	s_add_i32 s19, s50, s38
	v_add_u32_e32 v214, s18, v144
	v_lshl_add_u64 v[174:175], v[174:175], 0, s[24:25]
	s_mov_b32 m0, s19
	ds_read_b128 v[202:205], v214
	ds_read_b128 v[206:209], v214 offset:1024
	ds_read_b128 v[210:213], v214 offset:2048
	ds_read_b128 v[214:217], v214 offset:3072
	global_load_lds_dwordx4 v[174:175], off
	v_lshl_add_u64 v[174:175], v[218:219], 0, s[24:25]
	s_add_i32 m0, s19, 0x2000
	s_nop 0
	global_load_lds_dwordx4 v[174:175], off
	s_barrier
	s_waitcnt lgkmcnt(0)
	s_setprio 1
	s_waitcnt lgkmcnt(0)
	v_mfma_f32_16x16x32_bf16 v[116:119], v[202:205], v[154:157], v[116:119]
	v_mfma_f32_16x16x32_bf16 v[112:115], v[210:213], v[154:157], v[112:115]
	v_mfma_f32_16x16x32_bf16 v[100:103], v[202:205], v[162:165], v[100:103]
	v_mfma_f32_16x16x32_bf16 v[96:99], v[210:213], v[162:165], v[96:99]
	v_mfma_f32_16x16x32_bf16 v[84:87], v[202:205], v[170:173], v[84:87]
	v_mfma_f32_16x16x32_bf16 v[80:83], v[210:213], v[170:173], v[80:83]
	v_mfma_f32_16x16x32_bf16 v[68:71], v[202:205], v[194:197], v[68:71]
	v_mfma_f32_16x16x32_bf16 v[64:67], v[210:213], v[194:197], v[64:67]
	v_mfma_f32_16x16x32_bf16 v[116:119], v[206:209], v[158:161], v[116:119]
	v_mfma_f32_16x16x32_bf16 v[112:115], v[214:217], v[158:161], v[112:115]
	v_mfma_f32_16x16x32_bf16 v[100:103], v[206:209], v[166:169], v[100:103]
	v_mfma_f32_16x16x32_bf16 v[96:99], v[214:217], v[166:169], v[96:99]
	v_mfma_f32_16x16x32_bf16 v[84:87], v[206:209], v[190:193], v[84:87]
	v_mfma_f32_16x16x32_bf16 v[80:83], v[214:217], v[190:193], v[80:83]
	v_mfma_f32_16x16x32_bf16 v[68:71], v[206:209], v[198:201], v[68:71]
	v_mfma_f32_16x16x32_bf16 v[64:67], v[214:217], v[198:201], v[64:67]
	s_setprio 0
	s_mov_b32 m0, s45
	v_lshl_add_u64 v[174:175], v[220:221], 0, s[24:25]
	s_barrier
	ds_read_b128 v[154:157], v145 offset:49152
	ds_read_b128 v[158:161], v145 offset:50176
	ds_read_b128 v[162:165], v145 offset:51200
	ds_read_b128 v[166:169], v145 offset:52224
	ds_read_b128 v[170:173], v145 offset:53248
	ds_read_b128 v[190:193], v145 offset:54272
	ds_read_b128 v[194:197], v145 offset:55296
	ds_read_b128 v[198:201], v145 offset:56320
	global_load_lds_dwordx4 v[174:175], off
	v_lshl_add_u64 v[174:175], v[222:223], 0, s[24:25]
	s_mov_b32 m0, s46
	s_nop 0
	global_load_lds_dwordx4 v[174:175], off
	s_barrier
	s_waitcnt lgkmcnt(0)
	s_setprio 1
	s_waitcnt lgkmcnt(0)
	v_mfma_f32_16x16x32_bf16 v[60:63], v[134:137], v[154:157], v[60:63]
	v_mfma_f32_16x16x32_bf16 v[56:59], v[146:149], v[154:157], v[56:59]
	v_mfma_f32_16x16x32_bf16 v[44:47], v[134:137], v[162:165], v[44:47]
	v_mfma_f32_16x16x32_bf16 v[40:43], v[146:149], v[162:165], v[40:43]
	v_mfma_f32_16x16x32_bf16 v[28:31], v[134:137], v[170:173], v[28:31]
	v_mfma_f32_16x16x32_bf16 v[24:27], v[146:149], v[170:173], v[24:27]
	v_mfma_f32_16x16x32_bf16 v[12:15], v[134:137], v[194:197], v[12:15]
	v_mfma_f32_16x16x32_bf16 v[8:11], v[146:149], v[194:197], v[8:11]
	v_mfma_f32_16x16x32_bf16 v[60:63], v[138:141], v[158:161], v[60:63]
	v_mfma_f32_16x16x32_bf16 v[56:59], v[150:153], v[158:161], v[56:59]
	v_mfma_f32_16x16x32_bf16 v[44:47], v[138:141], v[166:169], v[44:47]
	v_mfma_f32_16x16x32_bf16 v[40:43], v[150:153], v[166:169], v[40:43]
	v_mfma_f32_16x16x32_bf16 v[28:31], v[138:141], v[190:193], v[28:31]
	v_mfma_f32_16x16x32_bf16 v[24:27], v[150:153], v[190:193], v[24:27]
	v_mfma_f32_16x16x32_bf16 v[12:15], v[138:141], v[198:201], v[12:15]
	v_mfma_f32_16x16x32_bf16 v[8:11], v[150:153], v[198:201], v[8:11]
	s_setprio 0
	s_barrier
	s_add_u32 s16, s16, 0x20080
	s_addc_u32 s17, s17, 0
	s_add_i32 s18, s18, s38
	v_lshl_add_u64 v[134:135], s[16:17], 0, v[176:177]
	s_mov_b32 m0, s18
	s_nop 0
	global_load_lds_dwordx4 v[134:135], off
	v_lshl_add_u64 v[134:135], s[16:17], 0, v[128:129]
	s_add_i32 m0, s18, 0x2000
	s_nop 0
	global_load_lds_dwordx4 v[134:135], off
	s_waitcnt vmcnt(6)
	s_barrier
	s_setprio 1
	v_mfma_f32_16x16x32_bf16 v[52:55], v[202:205], v[154:157], v[52:55]
	v_mfma_f32_16x16x32_bf16 v[48:51], v[210:213], v[154:157], v[48:51]
	v_mfma_f32_16x16x32_bf16 v[36:39], v[202:205], v[162:165], v[36:39]
	v_mfma_f32_16x16x32_bf16 v[32:35], v[210:213], v[162:165], v[32:35]
	v_mfma_f32_16x16x32_bf16 v[20:23], v[202:205], v[170:173], v[20:23]
	v_mfma_f32_16x16x32_bf16 v[16:19], v[210:213], v[170:173], v[16:19]
	v_mfma_f32_16x16x32_bf16 v[4:7], v[202:205], v[194:197], v[4:7]
	v_mfma_f32_16x16x32_bf16 v[0:3], v[210:213], v[194:197], v[0:3]
	v_mfma_f32_16x16x32_bf16 v[52:55], v[206:209], v[158:161], v[52:55]
	v_mfma_f32_16x16x32_bf16 v[48:51], v[214:217], v[158:161], v[48:51]
	v_mfma_f32_16x16x32_bf16 v[36:39], v[206:209], v[166:169], v[36:39]
	v_mfma_f32_16x16x32_bf16 v[32:35], v[214:217], v[166:169], v[32:35]
	v_mfma_f32_16x16x32_bf16 v[20:23], v[206:209], v[190:193], v[20:23]
	v_mfma_f32_16x16x32_bf16 v[16:19], v[214:217], v[190:193], v[16:19]
	v_mfma_f32_16x16x32_bf16 v[4:7], v[206:209], v[198:201], v[4:7]
	v_mfma_f32_16x16x32_bf16 v[0:3], v[214:217], v[198:201], v[0:3]
	s_setprio 0
	s_add_i32 s49, s49, 2
	s_add_u32 s14, s14, 0x100
	s_addc_u32 s15, s15, 0
	s_add_u32 s7, s7, 0x100
	s_addc_u32 s9, s9, 0
	s_cmp_gt_u32 s49, 5
	s_barrier
	s_cbranch_scc0 .LBB0_932
	s_lshl_b32 s7, s29, 6
	s_lshl_b32 s9, s2, 8
	s_add_i32 s7, s7, s9
	v_add_u32_e32 v140, s7, v142
	s_lshl_b32 s7, s44, 5
	s_lshl_b32 s9, s48, 8
	s_add_i32 s7, s7, s9
	v_lshl_add_u32 v141, v143, 2, s7
	s_mov_b32 s48, s6
	s_mov_b64 s[16:17], s[12:13]
	s_mov_b32 s2, s8
	s_mov_b64 s[14:15], s[10:11]
	v_lshlrev_b32_e32 v134, 2, v141
	global_load_dwordx4 v[240:243], v134, s[4:5]
	global_load_dwordx4 v[244:247], v134, s[4:5] offset:64
	global_load_dwordx4 v[252:255], v134, s[4:5] offset:512
	global_load_dwordx4 v[136:139], v134, s[4:5] offset:576
	v_lshlrev_b32_e32 v238, 10, v140
	v_lshl_add_u32 v238, v141, 1, v238
	v_lshlrev_b32_e32 v239, 11, v140
	v_lshl_add_u32 v239, v141, 1, v239
	v_add_u32_e32 v239, 0x4100400, v239
	global_load_dwordx2 v[190:191], v238, s[78:79]
	global_load_dwordx2 v[192:193], v238, s[78:79] offset:32
	global_load_dwordx2 v[194:195], v238, s[78:79] offset:256
	global_load_dwordx2 v[196:197], v238, s[78:79] offset:288
	v_add_u32_e32 v238, 0x4000, v238
	global_load_dwordx2 v[198:199], v238, s[78:79]
	global_load_dwordx2 v[200:201], v238, s[78:79] offset:32
	global_load_dwordx2 v[202:203], v238, s[78:79] offset:256
	global_load_dwordx2 v[204:205], v238, s[78:79] offset:288
	v_add_u32_e32 v238, 0x4000, v238
	global_load_dwordx2 v[206:207], v238, s[78:79]
	global_load_dwordx2 v[208:209], v238, s[78:79] offset:32
	global_load_dwordx2 v[210:211], v238, s[78:79] offset:256
	global_load_dwordx2 v[212:213], v238, s[78:79] offset:288
	v_add_u32_e32 v238, 0x4000, v238
	global_load_dwordx2 v[214:215], v238, s[78:79]
	global_load_dwordx2 v[216:217], v238, s[78:79] offset:32
	global_load_dwordx2 v[218:219], v238, s[78:79] offset:256
	global_load_dwordx2 v[220:221], v238, s[78:79] offset:288
	v_add_u32_e32 v238, 0x14000, v238
	global_load_dwordx2 v[222:223], v238, s[78:79]
	global_load_dwordx2 v[146:147], v238, s[78:79] offset:32
	global_load_dwordx2 v[148:149], v238, s[78:79] offset:256
	global_load_dwordx2 v[150:151], v238, s[78:79] offset:288
	v_add_u32_e32 v238, 0x4000, v238
	global_load_dwordx2 v[152:153], v238, s[78:79]
	global_load_dwordx2 v[154:155], v238, s[78:79] offset:32
	global_load_dwordx2 v[156:157], v238, s[78:79] offset:256
	global_load_dwordx2 v[158:159], v238, s[78:79] offset:288
	v_add_u32_e32 v238, 0x4000, v238
	global_load_dwordx2 v[160:161], v238, s[78:79]
	global_load_dwordx2 v[162:163], v238, s[78:79] offset:32
	global_load_dwordx2 v[164:165], v238, s[78:79] offset:256
	global_load_dwordx2 v[166:167], v238, s[78:79] offset:288
	v_add_u32_e32 v238, 0x4000, v238
	global_load_dwordx2 v[168:169], v238, s[78:79]
	global_load_dwordx2 v[170:171], v238, s[78:79] offset:32
	global_load_dwordx2 v[172:173], v238, s[78:79] offset:256
	global_load_dwordx2 v[174:175], v238, s[78:79] offset:288
	s_waitcnt vmcnt(31)
	v_pk_add_f32 v[124:125], v[124:125], v[240:241]
	v_pk_add_f32 v[126:127], v[126:127], v[242:243]
	v_mul_f32_e32 v124, 0xbfb8aa3b, v124
	v_mul_f32_e32 v125, 0xbfb8aa3b, v125
	v_mul_f32_e32 v126, 0xbfb8aa3b, v126
	v_mul_f32_e32 v127, 0xbfb8aa3b, v127
	v_exp_f32_e32 v124, v124
	v_exp_f32_e32 v125, v125
	v_exp_f32_e32 v126, v126
	v_exp_f32_e32 v127, v127
	v_lshlrev_b32_e32 v134, 16, v190
	v_and_b32_e32 v135, 0xffff0000, v190
	v_lshlrev_b32_e32 v140, 16, v191
	v_and_b32_e32 v141, 0xffff0000, v191
	v_add_f32_e32 v124, 1.0, v124
	v_add_f32_e32 v125, 1.0, v125
	v_add_f32_e32 v126, 1.0, v126
	v_add_f32_e32 v127, 1.0, v127
	v_rcp_f32_e32 v124, v124
	v_rcp_f32_e32 v125, v125
	v_rcp_f32_e32 v126, v126
	v_rcp_f32_e32 v127, v127
	s_nop 0
	v_pk_mul_f32 v[124:125], v[124:125], v[134:135]
	v_pk_mul_f32 v[126:127], v[126:127], v[140:141]
	v_cvt_pk_bf16_f32 v134, v124, v125
	v_cvt_pk_bf16_f32 v135, v126, v127
	global_store_dwordx2 v239, v[134:135], s[96:97]
	s_waitcnt vmcnt(31)
	v_pk_add_f32 v[120:121], v[120:121], v[244:245]
	v_pk_add_f32 v[122:123], v[122:123], v[246:247]
	v_mul_f32_e32 v120, 0xbfb8aa3b, v120
	v_mul_f32_e32 v121, 0xbfb8aa3b, v121
	v_mul_f32_e32 v122, 0xbfb8aa3b, v122
	v_mul_f32_e32 v123, 0xbfb8aa3b, v123
	v_exp_f32_e32 v120, v120
	v_exp_f32_e32 v121, v121
	v_exp_f32_e32 v122, v122
	v_exp_f32_e32 v123, v123
	v_lshlrev_b32_e32 v134, 16, v192
	v_and_b32_e32 v135, 0xffff0000, v192
	v_lshlrev_b32_e32 v140, 16, v193
	v_and_b32_e32 v141, 0xffff0000, v193
	v_add_f32_e32 v120, 1.0, v120
	v_add_f32_e32 v121, 1.0, v121
	v_add_f32_e32 v122, 1.0, v122
	v_add_f32_e32 v123, 1.0, v123
	v_rcp_f32_e32 v120, v120
	v_rcp_f32_e32 v121, v121
	v_rcp_f32_e32 v122, v122
	v_rcp_f32_e32 v123, v123
	s_nop 0
	v_pk_mul_f32 v[120:121], v[120:121], v[134:135]
	v_pk_mul_f32 v[122:123], v[122:123], v[140:141]
	v_cvt_pk_bf16_f32 v134, v120, v121
	v_cvt_pk_bf16_f32 v135, v122, v123
	global_store_dwordx2 v239, v[134:135], s[96:97] offset:32
	s_waitcnt vmcnt(31)
	v_pk_add_f32 v[116:117], v[116:117], v[252:253]
	v_pk_add_f32 v[118:119], v[118:119], v[254:255]
	v_mul_f32_e32 v116, 0xbfb8aa3b, v116
	v_mul_f32_e32 v117, 0xbfb8aa3b, v117
	v_mul_f32_e32 v118, 0xbfb8aa3b, v118
	v_mul_f32_e32 v119, 0xbfb8aa3b, v119
	v_exp_f32_e32 v116, v116
	v_exp_f32_e32 v117, v117
	v_exp_f32_e32 v118, v118
	v_exp_f32_e32 v119, v119
	v_lshlrev_b32_e32 v134, 16, v194
	v_and_b32_e32 v135, 0xffff0000, v194
	v_lshlrev_b32_e32 v140, 16, v195
	v_and_b32_e32 v141, 0xffff0000, v195
	v_add_f32_e32 v116, 1.0, v116
	v_add_f32_e32 v117, 1.0, v117
	v_add_f32_e32 v118, 1.0, v118
	v_add_f32_e32 v119, 1.0, v119
	v_rcp_f32_e32 v116, v116
	v_rcp_f32_e32 v117, v117
	v_rcp_f32_e32 v118, v118
	v_rcp_f32_e32 v119, v119
	s_nop 0
	v_pk_mul_f32 v[116:117], v[116:117], v[134:135]
	v_pk_mul_f32 v[118:119], v[118:119], v[140:141]
	v_cvt_pk_bf16_f32 v134, v116, v117
	v_cvt_pk_bf16_f32 v135, v118, v119
	global_store_dwordx2 v239, v[134:135], s[96:97] offset:256
	s_waitcnt vmcnt(31)
	v_pk_add_f32 v[112:113], v[112:113], v[136:137]
	v_pk_add_f32 v[114:115], v[114:115], v[138:139]
	v_mul_f32_e32 v112, 0xbfb8aa3b, v112
	v_mul_f32_e32 v113, 0xbfb8aa3b, v113
	v_mul_f32_e32 v114, 0xbfb8aa3b, v114
	v_mul_f32_e32 v115, 0xbfb8aa3b, v115
	v_exp_f32_e32 v112, v112
	v_exp_f32_e32 v113, v113
	v_exp_f32_e32 v114, v114
	v_exp_f32_e32 v115, v115
	v_lshlrev_b32_e32 v134, 16, v196
	v_and_b32_e32 v135, 0xffff0000, v196
	v_lshlrev_b32_e32 v140, 16, v197
	v_and_b32_e32 v141, 0xffff0000, v197
	v_add_f32_e32 v112, 1.0, v112
	v_add_f32_e32 v113, 1.0, v113
	v_add_f32_e32 v114, 1.0, v114
	v_add_f32_e32 v115, 1.0, v115
	v_rcp_f32_e32 v112, v112
	v_rcp_f32_e32 v113, v113
	v_rcp_f32_e32 v114, v114
	v_rcp_f32_e32 v115, v115
	s_nop 0
	v_pk_mul_f32 v[112:113], v[112:113], v[134:135]
	v_pk_mul_f32 v[114:115], v[114:115], v[140:141]
	v_cvt_pk_bf16_f32 v134, v112, v113
	v_cvt_pk_bf16_f32 v135, v114, v115
	global_store_dwordx2 v239, v[134:135], s[96:97] offset:288
	v_add_u32_e32 v239, 0x8000, v239
	s_waitcnt vmcnt(31)
	v_pk_add_f32 v[108:109], v[108:109], v[240:241]
	v_pk_add_f32 v[110:111], v[110:111], v[242:243]
	v_mul_f32_e32 v108, 0xbfb8aa3b, v108
	v_mul_f32_e32 v109, 0xbfb8aa3b, v109
	v_mul_f32_e32 v110, 0xbfb8aa3b, v110
	v_mul_f32_e32 v111, 0xbfb8aa3b, v111
	v_exp_f32_e32 v108, v108
	v_exp_f32_e32 v109, v109
	v_exp_f32_e32 v110, v110
	v_exp_f32_e32 v111, v111
	v_lshlrev_b32_e32 v134, 16, v198
	v_and_b32_e32 v135, 0xffff0000, v198
	v_lshlrev_b32_e32 v140, 16, v199
	v_and_b32_e32 v141, 0xffff0000, v199
	v_add_f32_e32 v108, 1.0, v108
	v_add_f32_e32 v109, 1.0, v109
	v_add_f32_e32 v110, 1.0, v110
	v_add_f32_e32 v111, 1.0, v111
	v_rcp_f32_e32 v108, v108
	v_rcp_f32_e32 v109, v109
	v_rcp_f32_e32 v110, v110
	v_rcp_f32_e32 v111, v111
	s_nop 0
	v_pk_mul_f32 v[108:109], v[108:109], v[134:135]
	v_pk_mul_f32 v[110:111], v[110:111], v[140:141]
	v_cvt_pk_bf16_f32 v134, v108, v109
	v_cvt_pk_bf16_f32 v135, v110, v111
	global_store_dwordx2 v239, v[134:135], s[96:97]
	s_waitcnt vmcnt(31)
	v_pk_add_f32 v[104:105], v[104:105], v[244:245]
	v_pk_add_f32 v[106:107], v[106:107], v[246:247]
	v_mul_f32_e32 v104, 0xbfb8aa3b, v104
	v_mul_f32_e32 v105, 0xbfb8aa3b, v105
	v_mul_f32_e32 v106, 0xbfb8aa3b, v106
	v_mul_f32_e32 v107, 0xbfb8aa3b, v107
	v_exp_f32_e32 v104, v104
	v_exp_f32_e32 v105, v105
	v_exp_f32_e32 v106, v106
	v_exp_f32_e32 v107, v107
	v_lshlrev_b32_e32 v134, 16, v200
	v_and_b32_e32 v135, 0xffff0000, v200
	v_lshlrev_b32_e32 v140, 16, v201
	v_and_b32_e32 v141, 0xffff0000, v201
	v_add_f32_e32 v104, 1.0, v104
	v_add_f32_e32 v105, 1.0, v105
	v_add_f32_e32 v106, 1.0, v106
	v_add_f32_e32 v107, 1.0, v107
	v_rcp_f32_e32 v104, v104
	v_rcp_f32_e32 v105, v105
	v_rcp_f32_e32 v106, v106
	v_rcp_f32_e32 v107, v107
	s_nop 0
	v_pk_mul_f32 v[104:105], v[104:105], v[134:135]
	v_pk_mul_f32 v[106:107], v[106:107], v[140:141]
	v_cvt_pk_bf16_f32 v134, v104, v105
	v_cvt_pk_bf16_f32 v135, v106, v107
	global_store_dwordx2 v239, v[134:135], s[96:97] offset:32
	s_waitcnt vmcnt(31)
	v_pk_add_f32 v[100:101], v[100:101], v[252:253]
	v_pk_add_f32 v[102:103], v[102:103], v[254:255]
	v_mul_f32_e32 v100, 0xbfb8aa3b, v100
	v_mul_f32_e32 v101, 0xbfb8aa3b, v101
	v_mul_f32_e32 v102, 0xbfb8aa3b, v102
	v_mul_f32_e32 v103, 0xbfb8aa3b, v103
	v_exp_f32_e32 v100, v100
	v_exp_f32_e32 v101, v101
	v_exp_f32_e32 v102, v102
	v_exp_f32_e32 v103, v103
	v_lshlrev_b32_e32 v134, 16, v202
	v_and_b32_e32 v135, 0xffff0000, v202
	v_lshlrev_b32_e32 v140, 16, v203
	v_and_b32_e32 v141, 0xffff0000, v203
	v_add_f32_e32 v100, 1.0, v100
	v_add_f32_e32 v101, 1.0, v101
	v_add_f32_e32 v102, 1.0, v102
	v_add_f32_e32 v103, 1.0, v103
	v_rcp_f32_e32 v100, v100
	v_rcp_f32_e32 v101, v101
	v_rcp_f32_e32 v102, v102
	v_rcp_f32_e32 v103, v103
	s_nop 0
	v_pk_mul_f32 v[100:101], v[100:101], v[134:135]
	v_pk_mul_f32 v[102:103], v[102:103], v[140:141]
	v_cvt_pk_bf16_f32 v134, v100, v101
	v_cvt_pk_bf16_f32 v135, v102, v103
	global_store_dwordx2 v239, v[134:135], s[96:97] offset:256
	s_waitcnt vmcnt(31)
	v_pk_add_f32 v[96:97], v[96:97], v[136:137]
	v_pk_add_f32 v[98:99], v[98:99], v[138:139]
	v_mul_f32_e32 v96, 0xbfb8aa3b, v96
	v_mul_f32_e32 v97, 0xbfb8aa3b, v97
	v_mul_f32_e32 v98, 0xbfb8aa3b, v98
	v_mul_f32_e32 v99, 0xbfb8aa3b, v99
	v_exp_f32_e32 v96, v96
	v_exp_f32_e32 v97, v97
	v_exp_f32_e32 v98, v98
	v_exp_f32_e32 v99, v99
	v_lshlrev_b32_e32 v134, 16, v204
	v_and_b32_e32 v135, 0xffff0000, v204
	v_lshlrev_b32_e32 v140, 16, v205
	v_and_b32_e32 v141, 0xffff0000, v205
	v_add_f32_e32 v96, 1.0, v96
	v_add_f32_e32 v97, 1.0, v97
	v_add_f32_e32 v98, 1.0, v98
	v_add_f32_e32 v99, 1.0, v99
	v_rcp_f32_e32 v96, v96
	v_rcp_f32_e32 v97, v97
	v_rcp_f32_e32 v98, v98
	v_rcp_f32_e32 v99, v99
	s_nop 0
	v_pk_mul_f32 v[96:97], v[96:97], v[134:135]
	v_pk_mul_f32 v[98:99], v[98:99], v[140:141]
	v_cvt_pk_bf16_f32 v134, v96, v97
	v_cvt_pk_bf16_f32 v135, v98, v99
	global_store_dwordx2 v239, v[134:135], s[96:97] offset:288
	v_add_u32_e32 v239, 0x8000, v239
	s_waitcnt vmcnt(31)
	v_pk_add_f32 v[92:93], v[92:93], v[240:241]
	v_pk_add_f32 v[94:95], v[94:95], v[242:243]
	v_mul_f32_e32 v92, 0xbfb8aa3b, v92
	v_mul_f32_e32 v93, 0xbfb8aa3b, v93
	v_mul_f32_e32 v94, 0xbfb8aa3b, v94
	v_mul_f32_e32 v95, 0xbfb8aa3b, v95
	v_exp_f32_e32 v92, v92
	v_exp_f32_e32 v93, v93
	v_exp_f32_e32 v94, v94
	v_exp_f32_e32 v95, v95
	v_lshlrev_b32_e32 v134, 16, v206
	v_and_b32_e32 v135, 0xffff0000, v206
	v_lshlrev_b32_e32 v140, 16, v207
	v_and_b32_e32 v141, 0xffff0000, v207
	v_add_f32_e32 v92, 1.0, v92
	v_add_f32_e32 v93, 1.0, v93
	v_add_f32_e32 v94, 1.0, v94
	v_add_f32_e32 v95, 1.0, v95
	v_rcp_f32_e32 v92, v92
	v_rcp_f32_e32 v93, v93
	v_rcp_f32_e32 v94, v94
	v_rcp_f32_e32 v95, v95
	s_nop 0
	v_pk_mul_f32 v[92:93], v[92:93], v[134:135]
	v_pk_mul_f32 v[94:95], v[94:95], v[140:141]
	v_cvt_pk_bf16_f32 v134, v92, v93
	v_cvt_pk_bf16_f32 v135, v94, v95
	global_store_dwordx2 v239, v[134:135], s[96:97]
	s_waitcnt vmcnt(31)
	v_pk_add_f32 v[88:89], v[88:89], v[244:245]
	v_pk_add_f32 v[90:91], v[90:91], v[246:247]
	v_mul_f32_e32 v88, 0xbfb8aa3b, v88
	v_mul_f32_e32 v89, 0xbfb8aa3b, v89
	v_mul_f32_e32 v90, 0xbfb8aa3b, v90
	v_mul_f32_e32 v91, 0xbfb8aa3b, v91
	v_exp_f32_e32 v88, v88
	v_exp_f32_e32 v89, v89
	v_exp_f32_e32 v90, v90
	v_exp_f32_e32 v91, v91
	v_lshlrev_b32_e32 v134, 16, v208
	v_and_b32_e32 v135, 0xffff0000, v208
	v_lshlrev_b32_e32 v140, 16, v209
	v_and_b32_e32 v141, 0xffff0000, v209
	v_add_f32_e32 v88, 1.0, v88
	v_add_f32_e32 v89, 1.0, v89
	v_add_f32_e32 v90, 1.0, v90
	v_add_f32_e32 v91, 1.0, v91
	v_rcp_f32_e32 v88, v88
	v_rcp_f32_e32 v89, v89
	v_rcp_f32_e32 v90, v90
	v_rcp_f32_e32 v91, v91
	s_nop 0
	v_pk_mul_f32 v[88:89], v[88:89], v[134:135]
	v_pk_mul_f32 v[90:91], v[90:91], v[140:141]
	v_cvt_pk_bf16_f32 v134, v88, v89
	v_cvt_pk_bf16_f32 v135, v90, v91
	global_store_dwordx2 v239, v[134:135], s[96:97] offset:32
	s_waitcnt vmcnt(31)
	v_pk_add_f32 v[84:85], v[84:85], v[252:253]
	v_pk_add_f32 v[86:87], v[86:87], v[254:255]
	v_mul_f32_e32 v84, 0xbfb8aa3b, v84
	v_mul_f32_e32 v85, 0xbfb8aa3b, v85
	v_mul_f32_e32 v86, 0xbfb8aa3b, v86
	v_mul_f32_e32 v87, 0xbfb8aa3b, v87
	v_exp_f32_e32 v84, v84
	v_exp_f32_e32 v85, v85
	v_exp_f32_e32 v86, v86
	v_exp_f32_e32 v87, v87
	v_lshlrev_b32_e32 v134, 16, v210
	v_and_b32_e32 v135, 0xffff0000, v210
	v_lshlrev_b32_e32 v140, 16, v211
	v_and_b32_e32 v141, 0xffff0000, v211
	v_add_f32_e32 v84, 1.0, v84
	v_add_f32_e32 v85, 1.0, v85
	v_add_f32_e32 v86, 1.0, v86
	v_add_f32_e32 v87, 1.0, v87
	v_rcp_f32_e32 v84, v84
	v_rcp_f32_e32 v85, v85
	v_rcp_f32_e32 v86, v86
	v_rcp_f32_e32 v87, v87
	s_nop 0
	v_pk_mul_f32 v[84:85], v[84:85], v[134:135]
	v_pk_mul_f32 v[86:87], v[86:87], v[140:141]
	v_cvt_pk_bf16_f32 v134, v84, v85
	v_cvt_pk_bf16_f32 v135, v86, v87
	global_store_dwordx2 v239, v[134:135], s[96:97] offset:256
	s_waitcnt vmcnt(31)
	v_pk_add_f32 v[80:81], v[80:81], v[136:137]
	v_pk_add_f32 v[82:83], v[82:83], v[138:139]
	v_mul_f32_e32 v80, 0xbfb8aa3b, v80
	v_mul_f32_e32 v81, 0xbfb8aa3b, v81
	v_mul_f32_e32 v82, 0xbfb8aa3b, v82
	v_mul_f32_e32 v83, 0xbfb8aa3b, v83
	v_exp_f32_e32 v80, v80
	v_exp_f32_e32 v81, v81
	v_exp_f32_e32 v82, v82
	v_exp_f32_e32 v83, v83
	v_lshlrev_b32_e32 v134, 16, v212
	v_and_b32_e32 v135, 0xffff0000, v212
	v_lshlrev_b32_e32 v140, 16, v213
	v_and_b32_e32 v141, 0xffff0000, v213
	v_add_f32_e32 v80, 1.0, v80
	v_add_f32_e32 v81, 1.0, v81
	v_add_f32_e32 v82, 1.0, v82
	v_add_f32_e32 v83, 1.0, v83
	v_rcp_f32_e32 v80, v80
	v_rcp_f32_e32 v81, v81
	v_rcp_f32_e32 v82, v82
	v_rcp_f32_e32 v83, v83
	s_nop 0
	v_pk_mul_f32 v[80:81], v[80:81], v[134:135]
	v_pk_mul_f32 v[82:83], v[82:83], v[140:141]
	v_cvt_pk_bf16_f32 v134, v80, v81
	v_cvt_pk_bf16_f32 v135, v82, v83
	global_store_dwordx2 v239, v[134:135], s[96:97] offset:288
	v_add_u32_e32 v239, 0x8000, v239
	s_waitcnt vmcnt(31)
	v_pk_add_f32 v[76:77], v[76:77], v[240:241]
	v_pk_add_f32 v[78:79], v[78:79], v[242:243]
	v_mul_f32_e32 v76, 0xbfb8aa3b, v76
	v_mul_f32_e32 v77, 0xbfb8aa3b, v77
	v_mul_f32_e32 v78, 0xbfb8aa3b, v78
	v_mul_f32_e32 v79, 0xbfb8aa3b, v79
	v_exp_f32_e32 v76, v76
	v_exp_f32_e32 v77, v77
	v_exp_f32_e32 v78, v78
	v_exp_f32_e32 v79, v79
	v_lshlrev_b32_e32 v134, 16, v214
	v_and_b32_e32 v135, 0xffff0000, v214
	v_lshlrev_b32_e32 v140, 16, v215
	v_and_b32_e32 v141, 0xffff0000, v215
	v_add_f32_e32 v76, 1.0, v76
	v_add_f32_e32 v77, 1.0, v77
	v_add_f32_e32 v78, 1.0, v78
	v_add_f32_e32 v79, 1.0, v79
	v_rcp_f32_e32 v76, v76
	v_rcp_f32_e32 v77, v77
	v_rcp_f32_e32 v78, v78
	v_rcp_f32_e32 v79, v79
	s_nop 0
	v_pk_mul_f32 v[76:77], v[76:77], v[134:135]
	v_pk_mul_f32 v[78:79], v[78:79], v[140:141]
	v_cvt_pk_bf16_f32 v134, v76, v77
	v_cvt_pk_bf16_f32 v135, v78, v79
	global_store_dwordx2 v239, v[134:135], s[96:97]
	s_waitcnt vmcnt(31)
	v_pk_add_f32 v[72:73], v[72:73], v[244:245]
	v_pk_add_f32 v[74:75], v[74:75], v[246:247]
	v_mul_f32_e32 v72, 0xbfb8aa3b, v72
	v_mul_f32_e32 v73, 0xbfb8aa3b, v73
	v_mul_f32_e32 v74, 0xbfb8aa3b, v74
	v_mul_f32_e32 v75, 0xbfb8aa3b, v75
	v_exp_f32_e32 v72, v72
	v_exp_f32_e32 v73, v73
	v_exp_f32_e32 v74, v74
	v_exp_f32_e32 v75, v75
	v_lshlrev_b32_e32 v134, 16, v216
	v_and_b32_e32 v135, 0xffff0000, v216
	v_lshlrev_b32_e32 v140, 16, v217
	v_and_b32_e32 v141, 0xffff0000, v217
	v_add_f32_e32 v72, 1.0, v72
	v_add_f32_e32 v73, 1.0, v73
	v_add_f32_e32 v74, 1.0, v74
	v_add_f32_e32 v75, 1.0, v75
	v_rcp_f32_e32 v72, v72
	v_rcp_f32_e32 v73, v73
	v_rcp_f32_e32 v74, v74
	v_rcp_f32_e32 v75, v75
	s_nop 0
	v_pk_mul_f32 v[72:73], v[72:73], v[134:135]
	v_pk_mul_f32 v[74:75], v[74:75], v[140:141]
	v_cvt_pk_bf16_f32 v134, v72, v73
	v_cvt_pk_bf16_f32 v135, v74, v75
	global_store_dwordx2 v239, v[134:135], s[96:97] offset:32
	s_waitcnt vmcnt(31)
	v_pk_add_f32 v[68:69], v[68:69], v[252:253]
	v_pk_add_f32 v[70:71], v[70:71], v[254:255]
	v_mul_f32_e32 v68, 0xbfb8aa3b, v68
	v_mul_f32_e32 v69, 0xbfb8aa3b, v69
	v_mul_f32_e32 v70, 0xbfb8aa3b, v70
	v_mul_f32_e32 v71, 0xbfb8aa3b, v71
	v_exp_f32_e32 v68, v68
	v_exp_f32_e32 v69, v69
	v_exp_f32_e32 v70, v70
	v_exp_f32_e32 v71, v71
	v_lshlrev_b32_e32 v134, 16, v218
	v_and_b32_e32 v135, 0xffff0000, v218
	v_lshlrev_b32_e32 v140, 16, v219
	v_and_b32_e32 v141, 0xffff0000, v219
	v_add_f32_e32 v68, 1.0, v68
	v_add_f32_e32 v69, 1.0, v69
	v_add_f32_e32 v70, 1.0, v70
	v_add_f32_e32 v71, 1.0, v71
	v_rcp_f32_e32 v68, v68
	v_rcp_f32_e32 v69, v69
	v_rcp_f32_e32 v70, v70
	v_rcp_f32_e32 v71, v71
	s_nop 0
	v_pk_mul_f32 v[68:69], v[68:69], v[134:135]
	v_pk_mul_f32 v[70:71], v[70:71], v[140:141]
	v_cvt_pk_bf16_f32 v134, v68, v69
	v_cvt_pk_bf16_f32 v135, v70, v71
	global_store_dwordx2 v239, v[134:135], s[96:97] offset:256
	s_waitcnt vmcnt(31)
	v_pk_add_f32 v[64:65], v[64:65], v[136:137]
	v_pk_add_f32 v[66:67], v[66:67], v[138:139]
	v_mul_f32_e32 v64, 0xbfb8aa3b, v64
	v_mul_f32_e32 v65, 0xbfb8aa3b, v65
	v_mul_f32_e32 v66, 0xbfb8aa3b, v66
	v_mul_f32_e32 v67, 0xbfb8aa3b, v67
	v_exp_f32_e32 v64, v64
	v_exp_f32_e32 v65, v65
	v_exp_f32_e32 v66, v66
	v_exp_f32_e32 v67, v67
	v_lshlrev_b32_e32 v134, 16, v220
	v_and_b32_e32 v135, 0xffff0000, v220
	v_lshlrev_b32_e32 v140, 16, v221
	v_and_b32_e32 v141, 0xffff0000, v221
	v_add_f32_e32 v64, 1.0, v64
	v_add_f32_e32 v65, 1.0, v65
	v_add_f32_e32 v66, 1.0, v66
	v_add_f32_e32 v67, 1.0, v67
	v_rcp_f32_e32 v64, v64
	v_rcp_f32_e32 v65, v65
	v_rcp_f32_e32 v66, v66
	v_rcp_f32_e32 v67, v67
	s_nop 0
	v_pk_mul_f32 v[64:65], v[64:65], v[134:135]
	v_pk_mul_f32 v[66:67], v[66:67], v[140:141]
	v_cvt_pk_bf16_f32 v134, v64, v65
	v_cvt_pk_bf16_f32 v135, v66, v67
	global_store_dwordx2 v239, v[134:135], s[96:97] offset:288
	v_add_u32_e32 v239, 0x28000, v239
	s_waitcnt vmcnt(31)
	v_pk_add_f32 v[60:61], v[60:61], v[240:241]
	v_pk_add_f32 v[62:63], v[62:63], v[242:243]
	v_mul_f32_e32 v60, 0xbfb8aa3b, v60
	v_mul_f32_e32 v61, 0xbfb8aa3b, v61
	v_mul_f32_e32 v62, 0xbfb8aa3b, v62
	v_mul_f32_e32 v63, 0xbfb8aa3b, v63
	v_exp_f32_e32 v60, v60
	v_exp_f32_e32 v61, v61
	v_exp_f32_e32 v62, v62
	v_exp_f32_e32 v63, v63
	v_lshlrev_b32_e32 v134, 16, v222
	v_and_b32_e32 v135, 0xffff0000, v222
	v_lshlrev_b32_e32 v140, 16, v223
	v_and_b32_e32 v141, 0xffff0000, v223
	v_add_f32_e32 v60, 1.0, v60
	v_add_f32_e32 v61, 1.0, v61
	v_add_f32_e32 v62, 1.0, v62
	v_add_f32_e32 v63, 1.0, v63
	v_rcp_f32_e32 v60, v60
	v_rcp_f32_e32 v61, v61
	v_rcp_f32_e32 v62, v62
	v_rcp_f32_e32 v63, v63
	s_nop 0
	v_pk_mul_f32 v[60:61], v[60:61], v[134:135]
	v_pk_mul_f32 v[62:63], v[62:63], v[140:141]
	v_cvt_pk_bf16_f32 v134, v60, v61
	v_cvt_pk_bf16_f32 v135, v62, v63
	global_store_dwordx2 v239, v[134:135], s[96:97]
	s_waitcnt vmcnt(31)
	v_pk_add_f32 v[56:57], v[56:57], v[244:245]
	v_pk_add_f32 v[58:59], v[58:59], v[246:247]
	v_mul_f32_e32 v56, 0xbfb8aa3b, v56
	v_mul_f32_e32 v57, 0xbfb8aa3b, v57
	v_mul_f32_e32 v58, 0xbfb8aa3b, v58
	v_mul_f32_e32 v59, 0xbfb8aa3b, v59
	v_exp_f32_e32 v56, v56
	v_exp_f32_e32 v57, v57
	v_exp_f32_e32 v58, v58
	v_exp_f32_e32 v59, v59
	v_lshlrev_b32_e32 v134, 16, v146
	v_and_b32_e32 v135, 0xffff0000, v146
	v_lshlrev_b32_e32 v140, 16, v147
	v_and_b32_e32 v141, 0xffff0000, v147
	v_add_f32_e32 v56, 1.0, v56
	v_add_f32_e32 v57, 1.0, v57
	v_add_f32_e32 v58, 1.0, v58
	v_add_f32_e32 v59, 1.0, v59
	v_rcp_f32_e32 v56, v56
	v_rcp_f32_e32 v57, v57
	v_rcp_f32_e32 v58, v58
	v_rcp_f32_e32 v59, v59
	s_nop 0
	v_pk_mul_f32 v[56:57], v[56:57], v[134:135]
	v_pk_mul_f32 v[58:59], v[58:59], v[140:141]
	v_cvt_pk_bf16_f32 v134, v56, v57
	v_cvt_pk_bf16_f32 v135, v58, v59
	global_store_dwordx2 v239, v[134:135], s[96:97] offset:32
	s_waitcnt vmcnt(31)
	v_pk_add_f32 v[52:53], v[52:53], v[252:253]
	v_pk_add_f32 v[54:55], v[54:55], v[254:255]
	v_mul_f32_e32 v52, 0xbfb8aa3b, v52
	v_mul_f32_e32 v53, 0xbfb8aa3b, v53
	v_mul_f32_e32 v54, 0xbfb8aa3b, v54
	v_mul_f32_e32 v55, 0xbfb8aa3b, v55
	v_exp_f32_e32 v52, v52
	v_exp_f32_e32 v53, v53
	v_exp_f32_e32 v54, v54
	v_exp_f32_e32 v55, v55
	v_lshlrev_b32_e32 v134, 16, v148
	v_and_b32_e32 v135, 0xffff0000, v148
	v_lshlrev_b32_e32 v140, 16, v149
	v_and_b32_e32 v141, 0xffff0000, v149
	v_add_f32_e32 v52, 1.0, v52
	v_add_f32_e32 v53, 1.0, v53
	v_add_f32_e32 v54, 1.0, v54
	v_add_f32_e32 v55, 1.0, v55
	v_rcp_f32_e32 v52, v52
	v_rcp_f32_e32 v53, v53
	v_rcp_f32_e32 v54, v54
	v_rcp_f32_e32 v55, v55
	s_nop 0
	v_pk_mul_f32 v[52:53], v[52:53], v[134:135]
	v_pk_mul_f32 v[54:55], v[54:55], v[140:141]
	v_cvt_pk_bf16_f32 v134, v52, v53
	v_cvt_pk_bf16_f32 v135, v54, v55
	global_store_dwordx2 v239, v[134:135], s[96:97] offset:256
	s_waitcnt vmcnt(31)
	v_pk_add_f32 v[48:49], v[48:49], v[136:137]
	v_pk_add_f32 v[50:51], v[50:51], v[138:139]
	v_mul_f32_e32 v48, 0xbfb8aa3b, v48
	v_mul_f32_e32 v49, 0xbfb8aa3b, v49
	v_mul_f32_e32 v50, 0xbfb8aa3b, v50
	v_mul_f32_e32 v51, 0xbfb8aa3b, v51
	v_exp_f32_e32 v48, v48
	v_exp_f32_e32 v49, v49
	v_exp_f32_e32 v50, v50
	v_exp_f32_e32 v51, v51
	v_lshlrev_b32_e32 v134, 16, v150
	v_and_b32_e32 v135, 0xffff0000, v150
	v_lshlrev_b32_e32 v140, 16, v151
	v_and_b32_e32 v141, 0xffff0000, v151
	v_add_f32_e32 v48, 1.0, v48
	v_add_f32_e32 v49, 1.0, v49
	v_add_f32_e32 v50, 1.0, v50
	v_add_f32_e32 v51, 1.0, v51
	v_rcp_f32_e32 v48, v48
	v_rcp_f32_e32 v49, v49
	v_rcp_f32_e32 v50, v50
	v_rcp_f32_e32 v51, v51
	s_nop 0
	v_pk_mul_f32 v[48:49], v[48:49], v[134:135]
	v_pk_mul_f32 v[50:51], v[50:51], v[140:141]
	v_cvt_pk_bf16_f32 v134, v48, v49
	v_cvt_pk_bf16_f32 v135, v50, v51
	global_store_dwordx2 v239, v[134:135], s[96:97] offset:288
	v_add_u32_e32 v239, 0x8000, v239
	s_waitcnt vmcnt(31)
	v_pk_add_f32 v[44:45], v[44:45], v[240:241]
	v_pk_add_f32 v[46:47], v[46:47], v[242:243]
	v_mul_f32_e32 v44, 0xbfb8aa3b, v44
	v_mul_f32_e32 v45, 0xbfb8aa3b, v45
	v_mul_f32_e32 v46, 0xbfb8aa3b, v46
	v_mul_f32_e32 v47, 0xbfb8aa3b, v47
	v_exp_f32_e32 v44, v44
	v_exp_f32_e32 v45, v45
	v_exp_f32_e32 v46, v46
	v_exp_f32_e32 v47, v47
	v_lshlrev_b32_e32 v134, 16, v152
	v_and_b32_e32 v135, 0xffff0000, v152
	v_lshlrev_b32_e32 v140, 16, v153
	v_and_b32_e32 v141, 0xffff0000, v153
	v_add_f32_e32 v44, 1.0, v44
	v_add_f32_e32 v45, 1.0, v45
	v_add_f32_e32 v46, 1.0, v46
	v_add_f32_e32 v47, 1.0, v47
	v_rcp_f32_e32 v44, v44
	v_rcp_f32_e32 v45, v45
	v_rcp_f32_e32 v46, v46
	v_rcp_f32_e32 v47, v47
	s_nop 0
	v_pk_mul_f32 v[44:45], v[44:45], v[134:135]
	v_pk_mul_f32 v[46:47], v[46:47], v[140:141]
	v_cvt_pk_bf16_f32 v134, v44, v45
	v_cvt_pk_bf16_f32 v135, v46, v47
	global_store_dwordx2 v239, v[134:135], s[96:97]
	s_waitcnt vmcnt(31)
	v_pk_add_f32 v[40:41], v[40:41], v[244:245]
	v_pk_add_f32 v[42:43], v[42:43], v[246:247]
	v_mul_f32_e32 v40, 0xbfb8aa3b, v40
	v_mul_f32_e32 v41, 0xbfb8aa3b, v41
	v_mul_f32_e32 v42, 0xbfb8aa3b, v42
	v_mul_f32_e32 v43, 0xbfb8aa3b, v43
	v_exp_f32_e32 v40, v40
	v_exp_f32_e32 v41, v41
	v_exp_f32_e32 v42, v42
	v_exp_f32_e32 v43, v43
	v_lshlrev_b32_e32 v134, 16, v154
	v_and_b32_e32 v135, 0xffff0000, v154
	v_lshlrev_b32_e32 v140, 16, v155
	v_and_b32_e32 v141, 0xffff0000, v155
	v_add_f32_e32 v40, 1.0, v40
	v_add_f32_e32 v41, 1.0, v41
	v_add_f32_e32 v42, 1.0, v42
	v_add_f32_e32 v43, 1.0, v43
	v_rcp_f32_e32 v40, v40
	v_rcp_f32_e32 v41, v41
	v_rcp_f32_e32 v42, v42
	v_rcp_f32_e32 v43, v43
	s_nop 0
	v_pk_mul_f32 v[40:41], v[40:41], v[134:135]
	v_pk_mul_f32 v[42:43], v[42:43], v[140:141]
	v_cvt_pk_bf16_f32 v134, v40, v41
	v_cvt_pk_bf16_f32 v135, v42, v43
	global_store_dwordx2 v239, v[134:135], s[96:97] offset:32
	s_waitcnt vmcnt(31)
	v_pk_add_f32 v[36:37], v[36:37], v[252:253]
	v_pk_add_f32 v[38:39], v[38:39], v[254:255]
	v_mul_f32_e32 v36, 0xbfb8aa3b, v36
	v_mul_f32_e32 v37, 0xbfb8aa3b, v37
	v_mul_f32_e32 v38, 0xbfb8aa3b, v38
	v_mul_f32_e32 v39, 0xbfb8aa3b, v39
	v_exp_f32_e32 v36, v36
	v_exp_f32_e32 v37, v37
	v_exp_f32_e32 v38, v38
	v_exp_f32_e32 v39, v39
	v_lshlrev_b32_e32 v134, 16, v156
	v_and_b32_e32 v135, 0xffff0000, v156
	v_lshlrev_b32_e32 v140, 16, v157
	v_and_b32_e32 v141, 0xffff0000, v157
	v_add_f32_e32 v36, 1.0, v36
	v_add_f32_e32 v37, 1.0, v37
	v_add_f32_e32 v38, 1.0, v38
	v_add_f32_e32 v39, 1.0, v39
	v_rcp_f32_e32 v36, v36
	v_rcp_f32_e32 v37, v37
	v_rcp_f32_e32 v38, v38
	v_rcp_f32_e32 v39, v39
	s_nop 0
	v_pk_mul_f32 v[36:37], v[36:37], v[134:135]
	v_pk_mul_f32 v[38:39], v[38:39], v[140:141]
	v_cvt_pk_bf16_f32 v134, v36, v37
	v_cvt_pk_bf16_f32 v135, v38, v39
	global_store_dwordx2 v239, v[134:135], s[96:97] offset:256
	s_waitcnt vmcnt(31)
	v_pk_add_f32 v[32:33], v[32:33], v[136:137]
	v_pk_add_f32 v[34:35], v[34:35], v[138:139]
	v_mul_f32_e32 v32, 0xbfb8aa3b, v32
	v_mul_f32_e32 v33, 0xbfb8aa3b, v33
	v_mul_f32_e32 v34, 0xbfb8aa3b, v34
	v_mul_f32_e32 v35, 0xbfb8aa3b, v35
	v_exp_f32_e32 v32, v32
	v_exp_f32_e32 v33, v33
	v_exp_f32_e32 v34, v34
	v_exp_f32_e32 v35, v35
	v_lshlrev_b32_e32 v134, 16, v158
	v_and_b32_e32 v135, 0xffff0000, v158
	v_lshlrev_b32_e32 v140, 16, v159
	v_and_b32_e32 v141, 0xffff0000, v159
	v_add_f32_e32 v32, 1.0, v32
	v_add_f32_e32 v33, 1.0, v33
	v_add_f32_e32 v34, 1.0, v34
	v_add_f32_e32 v35, 1.0, v35
	v_rcp_f32_e32 v32, v32
	v_rcp_f32_e32 v33, v33
	v_rcp_f32_e32 v34, v34
	v_rcp_f32_e32 v35, v35
	s_nop 0
	v_pk_mul_f32 v[32:33], v[32:33], v[134:135]
	v_pk_mul_f32 v[34:35], v[34:35], v[140:141]
	v_cvt_pk_bf16_f32 v134, v32, v33
	v_cvt_pk_bf16_f32 v135, v34, v35
	global_store_dwordx2 v239, v[134:135], s[96:97] offset:288
	v_add_u32_e32 v239, 0x8000, v239
	s_waitcnt vmcnt(31)
	v_pk_add_f32 v[28:29], v[28:29], v[240:241]
	v_pk_add_f32 v[30:31], v[30:31], v[242:243]
	v_mul_f32_e32 v28, 0xbfb8aa3b, v28
	v_mul_f32_e32 v29, 0xbfb8aa3b, v29
	v_mul_f32_e32 v30, 0xbfb8aa3b, v30
	v_mul_f32_e32 v31, 0xbfb8aa3b, v31
	v_exp_f32_e32 v28, v28
	v_exp_f32_e32 v29, v29
	v_exp_f32_e32 v30, v30
	v_exp_f32_e32 v31, v31
	v_lshlrev_b32_e32 v134, 16, v160
	v_and_b32_e32 v135, 0xffff0000, v160
	v_lshlrev_b32_e32 v140, 16, v161
	v_and_b32_e32 v141, 0xffff0000, v161
	v_add_f32_e32 v28, 1.0, v28
	v_add_f32_e32 v29, 1.0, v29
	v_add_f32_e32 v30, 1.0, v30
	v_add_f32_e32 v31, 1.0, v31
	v_rcp_f32_e32 v28, v28
	v_rcp_f32_e32 v29, v29
	v_rcp_f32_e32 v30, v30
	v_rcp_f32_e32 v31, v31
	s_nop 0
	v_pk_mul_f32 v[28:29], v[28:29], v[134:135]
	v_pk_mul_f32 v[30:31], v[30:31], v[140:141]
	v_cvt_pk_bf16_f32 v134, v28, v29
	v_cvt_pk_bf16_f32 v135, v30, v31
	global_store_dwordx2 v239, v[134:135], s[96:97]
	s_waitcnt vmcnt(31)
	v_pk_add_f32 v[24:25], v[24:25], v[244:245]
	v_pk_add_f32 v[26:27], v[26:27], v[246:247]
	v_mul_f32_e32 v24, 0xbfb8aa3b, v24
	v_mul_f32_e32 v25, 0xbfb8aa3b, v25
	v_mul_f32_e32 v26, 0xbfb8aa3b, v26
	v_mul_f32_e32 v27, 0xbfb8aa3b, v27
	v_exp_f32_e32 v24, v24
	v_exp_f32_e32 v25, v25
	v_exp_f32_e32 v26, v26
	v_exp_f32_e32 v27, v27
	v_lshlrev_b32_e32 v134, 16, v162
	v_and_b32_e32 v135, 0xffff0000, v162
	v_lshlrev_b32_e32 v140, 16, v163
	v_and_b32_e32 v141, 0xffff0000, v163
	v_add_f32_e32 v24, 1.0, v24
	v_add_f32_e32 v25, 1.0, v25
	v_add_f32_e32 v26, 1.0, v26
	v_add_f32_e32 v27, 1.0, v27
	v_rcp_f32_e32 v24, v24
	v_rcp_f32_e32 v25, v25
	v_rcp_f32_e32 v26, v26
	v_rcp_f32_e32 v27, v27
	s_nop 0
	v_pk_mul_f32 v[24:25], v[24:25], v[134:135]
	v_pk_mul_f32 v[26:27], v[26:27], v[140:141]
	v_cvt_pk_bf16_f32 v134, v24, v25
	v_cvt_pk_bf16_f32 v135, v26, v27
	global_store_dwordx2 v239, v[134:135], s[96:97] offset:32
	s_waitcnt vmcnt(31)
	v_pk_add_f32 v[20:21], v[20:21], v[252:253]
	v_pk_add_f32 v[22:23], v[22:23], v[254:255]
	v_mul_f32_e32 v20, 0xbfb8aa3b, v20
	v_mul_f32_e32 v21, 0xbfb8aa3b, v21
	v_mul_f32_e32 v22, 0xbfb8aa3b, v22
	v_mul_f32_e32 v23, 0xbfb8aa3b, v23
	v_exp_f32_e32 v20, v20
	v_exp_f32_e32 v21, v21
	v_exp_f32_e32 v22, v22
	v_exp_f32_e32 v23, v23
	v_lshlrev_b32_e32 v134, 16, v164
	v_and_b32_e32 v135, 0xffff0000, v164
	v_lshlrev_b32_e32 v140, 16, v165
	v_and_b32_e32 v141, 0xffff0000, v165
	v_add_f32_e32 v20, 1.0, v20
	v_add_f32_e32 v21, 1.0, v21
	v_add_f32_e32 v22, 1.0, v22
	v_add_f32_e32 v23, 1.0, v23
	v_rcp_f32_e32 v20, v20
	v_rcp_f32_e32 v21, v21
	v_rcp_f32_e32 v22, v22
	v_rcp_f32_e32 v23, v23
	s_nop 0
	v_pk_mul_f32 v[20:21], v[20:21], v[134:135]
	v_pk_mul_f32 v[22:23], v[22:23], v[140:141]
	v_cvt_pk_bf16_f32 v134, v20, v21
	v_cvt_pk_bf16_f32 v135, v22, v23
	global_store_dwordx2 v239, v[134:135], s[96:97] offset:256
	s_waitcnt vmcnt(31)
	v_pk_add_f32 v[16:17], v[16:17], v[136:137]
	v_pk_add_f32 v[18:19], v[18:19], v[138:139]
	v_mul_f32_e32 v16, 0xbfb8aa3b, v16
	v_mul_f32_e32 v17, 0xbfb8aa3b, v17
	v_mul_f32_e32 v18, 0xbfb8aa3b, v18
	v_mul_f32_e32 v19, 0xbfb8aa3b, v19
	v_exp_f32_e32 v16, v16
	v_exp_f32_e32 v17, v17
	v_exp_f32_e32 v18, v18
	v_exp_f32_e32 v19, v19
	v_lshlrev_b32_e32 v134, 16, v166
	v_and_b32_e32 v135, 0xffff0000, v166
	v_lshlrev_b32_e32 v140, 16, v167
	v_and_b32_e32 v141, 0xffff0000, v167
	v_add_f32_e32 v16, 1.0, v16
	v_add_f32_e32 v17, 1.0, v17
	v_add_f32_e32 v18, 1.0, v18
	v_add_f32_e32 v19, 1.0, v19
	v_rcp_f32_e32 v16, v16
	v_rcp_f32_e32 v17, v17
	v_rcp_f32_e32 v18, v18
	v_rcp_f32_e32 v19, v19
	s_nop 0
	v_pk_mul_f32 v[16:17], v[16:17], v[134:135]
	v_pk_mul_f32 v[18:19], v[18:19], v[140:141]
	v_cvt_pk_bf16_f32 v134, v16, v17
	v_cvt_pk_bf16_f32 v135, v18, v19
	global_store_dwordx2 v239, v[134:135], s[96:97] offset:288
	v_add_u32_e32 v239, 0x8000, v239
	s_waitcnt vmcnt(31)
	v_pk_add_f32 v[12:13], v[12:13], v[240:241]
	v_pk_add_f32 v[14:15], v[14:15], v[242:243]
	v_mul_f32_e32 v12, 0xbfb8aa3b, v12
	v_mul_f32_e32 v13, 0xbfb8aa3b, v13
	v_mul_f32_e32 v14, 0xbfb8aa3b, v14
	v_mul_f32_e32 v15, 0xbfb8aa3b, v15
	v_exp_f32_e32 v12, v12
	v_exp_f32_e32 v13, v13
	v_exp_f32_e32 v14, v14
	v_exp_f32_e32 v15, v15
	v_lshlrev_b32_e32 v134, 16, v168
	v_and_b32_e32 v135, 0xffff0000, v168
	v_lshlrev_b32_e32 v140, 16, v169
	v_and_b32_e32 v141, 0xffff0000, v169
	v_add_f32_e32 v12, 1.0, v12
	v_add_f32_e32 v13, 1.0, v13
	v_add_f32_e32 v14, 1.0, v14
	v_add_f32_e32 v15, 1.0, v15
	v_rcp_f32_e32 v12, v12
	v_rcp_f32_e32 v13, v13
	v_rcp_f32_e32 v14, v14
	v_rcp_f32_e32 v15, v15
	s_nop 0
	v_pk_mul_f32 v[12:13], v[12:13], v[134:135]
	v_pk_mul_f32 v[14:15], v[14:15], v[140:141]
	v_cvt_pk_bf16_f32 v134, v12, v13
	v_cvt_pk_bf16_f32 v135, v14, v15
	global_store_dwordx2 v239, v[134:135], s[96:97]
	s_waitcnt vmcnt(31)
	v_pk_add_f32 v[8:9], v[8:9], v[244:245]
	v_pk_add_f32 v[10:11], v[10:11], v[246:247]
	v_mul_f32_e32 v8, 0xbfb8aa3b, v8
	v_mul_f32_e32 v9, 0xbfb8aa3b, v9
	v_mul_f32_e32 v10, 0xbfb8aa3b, v10
	v_mul_f32_e32 v11, 0xbfb8aa3b, v11
	v_exp_f32_e32 v8, v8
	v_exp_f32_e32 v9, v9
	v_exp_f32_e32 v10, v10
	v_exp_f32_e32 v11, v11
	v_lshlrev_b32_e32 v134, 16, v170
	v_and_b32_e32 v135, 0xffff0000, v170
	v_lshlrev_b32_e32 v140, 16, v171
	v_and_b32_e32 v141, 0xffff0000, v171
	v_add_f32_e32 v8, 1.0, v8
	v_add_f32_e32 v9, 1.0, v9
	v_add_f32_e32 v10, 1.0, v10
	v_add_f32_e32 v11, 1.0, v11
	v_rcp_f32_e32 v8, v8
	v_rcp_f32_e32 v9, v9
	v_rcp_f32_e32 v10, v10
	v_rcp_f32_e32 v11, v11
	s_nop 0
	v_pk_mul_f32 v[8:9], v[8:9], v[134:135]
	v_pk_mul_f32 v[10:11], v[10:11], v[140:141]
	v_cvt_pk_bf16_f32 v134, v8, v9
	v_cvt_pk_bf16_f32 v135, v10, v11
	global_store_dwordx2 v239, v[134:135], s[96:97] offset:32
	s_waitcnt vmcnt(31)
	v_pk_add_f32 v[4:5], v[4:5], v[252:253]
	v_pk_add_f32 v[6:7], v[6:7], v[254:255]
	v_mul_f32_e32 v4, 0xbfb8aa3b, v4
	v_mul_f32_e32 v5, 0xbfb8aa3b, v5
	v_mul_f32_e32 v6, 0xbfb8aa3b, v6
	v_mul_f32_e32 v7, 0xbfb8aa3b, v7
	v_exp_f32_e32 v4, v4
	v_exp_f32_e32 v5, v5
	v_exp_f32_e32 v6, v6
	v_exp_f32_e32 v7, v7
	v_lshlrev_b32_e32 v134, 16, v172
	v_and_b32_e32 v135, 0xffff0000, v172
	v_lshlrev_b32_e32 v140, 16, v173
	v_and_b32_e32 v141, 0xffff0000, v173
	v_add_f32_e32 v4, 1.0, v4
	v_add_f32_e32 v5, 1.0, v5
	v_add_f32_e32 v6, 1.0, v6
	v_add_f32_e32 v7, 1.0, v7
	v_rcp_f32_e32 v4, v4
	v_rcp_f32_e32 v5, v5
	v_rcp_f32_e32 v6, v6
	v_rcp_f32_e32 v7, v7
	s_nop 0
	v_pk_mul_f32 v[4:5], v[4:5], v[134:135]
	v_pk_mul_f32 v[6:7], v[6:7], v[140:141]
	v_cvt_pk_bf16_f32 v134, v4, v5
	v_cvt_pk_bf16_f32 v135, v6, v7
	global_store_dwordx2 v239, v[134:135], s[96:97] offset:256
	s_waitcnt vmcnt(31)
	v_pk_add_f32 v[0:1], v[0:1], v[136:137]
	v_pk_add_f32 v[2:3], v[2:3], v[138:139]
	v_mul_f32_e32 v0, 0xbfb8aa3b, v0
	v_mul_f32_e32 v1, 0xbfb8aa3b, v1
	v_mul_f32_e32 v2, 0xbfb8aa3b, v2
	v_mul_f32_e32 v3, 0xbfb8aa3b, v3
	v_exp_f32_e32 v0, v0
	v_exp_f32_e32 v1, v1
	v_exp_f32_e32 v2, v2
	v_exp_f32_e32 v3, v3
	v_lshlrev_b32_e32 v134, 16, v174
	v_and_b32_e32 v135, 0xffff0000, v174
	v_lshlrev_b32_e32 v140, 16, v175
	v_and_b32_e32 v141, 0xffff0000, v175
	v_add_f32_e32 v0, 1.0, v0
	v_add_f32_e32 v1, 1.0, v1
	v_add_f32_e32 v2, 1.0, v2
	v_add_f32_e32 v3, 1.0, v3
	v_rcp_f32_e32 v0, v0
	v_rcp_f32_e32 v1, v1
	v_rcp_f32_e32 v2, v2
	v_rcp_f32_e32 v3, v3
	s_nop 0
	v_pk_mul_f32 v[0:1], v[0:1], v[134:135]
	v_pk_mul_f32 v[2:3], v[2:3], v[140:141]
	v_cvt_pk_bf16_f32 v134, v0, v1
	v_cvt_pk_bf16_f32 v135, v2, v3
	global_store_dwordx2 v239, v[134:135], s[96:97] offset:288
	s_and_b64 vcc, exec, s[40:41]
	s_cbranch_vccz .LBB0_925
	s_cmp_gt_u32 s90, 4
	s_cselect_b32 s36, 4, 0
	s_cmp_lt_u32 s21, s36
	s_cbranch_scc1 .Lwd_done
	v_readlane_b32 s37, v250, 58
	v_readlane_b32 s38, v250, 52
	v_readlane_b32 s39, v250, 53
	v_readfirstlane_b32 s40, v224
	v_and_b32_e32 v0, 63, v224
	s_lshr_b32 s40, s40, 6
	s_sub_u32 s41, s21, s36
	s_lshl_b32 s41, s41, 3
	s_add_u32 s40, s40, s41
	s_sub_u32 s41, s90, s36
	s_lshl_b32 s41, s41, 3
	v_lshlrev_b32_e32 v1, 2, v0
	v_add_u32_e32 v2, 0x1000, v1
	v_add_u32_e32 v3, 0x2000, v1
	v_add_u32_e32 v4, 0x3000, v1
	v_add_u32_e32 v5, 0x4000, v1
	v_add_u32_e32 v6, 0x5000, v1
	v_add_u32_e32 v7, 0x6000, v1
	v_add_u32_e32 v8, 0x7000, v1
	v_lshlrev_b32_e32 v9, 11, v0
	s_load_dwordx2 s[42:43], s[38:39], 0xf8
	s_add_u32 s44, s96, 0x1d9a9800
	s_addc_u32 s45, s97, 0
	s_lshl_b32 s47, s37, 23
	s_waitcnt lgkmcnt(0)
	s_add_u32 s42, s42, s47
	s_addc_u32 s43, s43, 0
	s_mov_b32 s60, s40
.Lwd_br_loop:
	s_cmp_ge_u32 s60, 0x1000
	s_cbranch_scc1 .Lwd_br_end
	s_lshr_b32 s54, s60, 10
	s_bfe_u32 s55, s60, 0x60004
	s_and_b32 s61, s60, 15
	s_lshl_b32 s47, s54, 21
	s_lshl_b32 s58, s55, 15
	s_add_u32 s47, s47, s58
	s_lshl_b32 s58, s61, 8
	s_add_u32 s47, s47, s58
	s_add_u32 s56, s42, s47
	s_addc_u32 s57, s43, 0
	global_load_dword v16, v1, s[56:57]
	global_load_dword v17, v2, s[56:57]
	global_load_dword v18, v3, s[56:57]
	global_load_dword v19, v4, s[56:57]
	global_load_dword v20, v5, s[56:57]
	global_load_dword v21, v6, s[56:57]
	global_load_dword v22, v7, s[56:57]
	global_load_dword v23, v8, s[56:57]
	s_lshr_b32 s58, s54, 1
	s_lshl_b32 s58, s58, 21
	s_and_b32 s59, s54, 1
	s_lshl_b32 s59, s59, 10
	s_add_u32 s58, s58, s59
	s_lshl_b32 s59, s61, 17
	s_add_u32 s58, s58, s59
	s_lshl_b32 s59, s55, 4
	s_add_u32 s58, s58, s59
	s_add_u32 s58, s44, s58
	s_addc_u32 s59, s45, 0
	s_waitcnt vmcnt(0)
	v_cvt_pk_bf16_f32 v16, v16, v17
	v_cvt_pk_bf16_f32 v17, v18, v19
	v_cvt_pk_bf16_f32 v18, v20, v21
	v_cvt_pk_bf16_f32 v19, v22, v23
	global_store_dwordx4 v9, v[16:19], s[58:59]
	s_add_u32 s60, s60, s41
	s_branch .Lwd_br_loop
.Lwd_br_end:
	s_load_dwordx2 s[42:43], s[38:39], 0x100
	s_add_u32 s44, s96, 0x1dda9800
	s_addc_u32 s45, s97, 0
	s_lshl_b32 s47, s37, 22
	s_waitcnt lgkmcnt(0)
	s_add_u32 s42, s42, s47
	s_addc_u32 s43, s43, 0
	s_mov_b32 s60, s40
.Lwd_out_loop:
	s_cmp_ge_u32 s60, 0x800
	s_cbranch_scc1 .Lwd_out_end
	s_lshr_b32 s55, s60, 4
	s_and_b32 s61, s60, 15
	s_lshl_b32 s47, s55, 15
	s_lshl_b32 s58, s61, 8
	s_add_u32 s47, s47, s58
	s_add_u32 s56, s42, s47
	s_addc_u32 s57, s43, 0
	global_load_dword v16, v1, s[56:57]
	global_load_dword v17, v2, s[56:57]
	global_load_dword v18, v3, s[56:57]
	global_load_dword v19, v4, s[56:57]
	global_load_dword v20, v5, s[56:57]
	global_load_dword v21, v6, s[56:57]
	global_load_dword v22, v7, s[56:57]
	global_load_dword v23, v8, s[56:57]
	s_lshl_b32 s58, s61, 17
	s_lshl_b32 s59, s55, 4
	s_add_u32 s58, s58, s59
	s_add_u32 s58, s44, s58
	s_addc_u32 s59, s45, 0
	s_waitcnt vmcnt(0)
	v_cvt_pk_bf16_f32 v16, v16, v17
	v_cvt_pk_bf16_f32 v17, v18, v19
	v_cvt_pk_bf16_f32 v18, v20, v21
	v_cvt_pk_bf16_f32 v19, v22, v23
	global_store_dwordx4 v9, v[16:19], s[58:59]
	s_add_u32 s60, s60, s41
	s_branch .Lwd_out_loop
.Lwd_out_end:
.Lwd_done:
	s_waitcnt vmcnt(0)
	s_cmpk_gt_u32 s22, 0xff
	s_cbranch_scc1 .LBB0_936
	s_barrier
